# A/B epilogue LayerNorm row sums: 48 ds_bpermute butterfly steps replaced by a DPP wave reduction (quad_perm, row_half_mirror, row_mirror, row_bcast) + readlane broadcast
# speedup vs baseline: 1.0192x; 1.0074x over previous
.LBB0_840:
	s_or_b64 exec, exec, s[10:11]
	s_nop 0
	v_lshl_or_b32 v148, v148, 11, v154
	v_add_u32_e32 v123, 0x1000, v148
	v_pk_mul_f32 v[118:119], v[82:83], v[82:83]
	v_pk_add_f32 v[120:121], v[82:83], v[84:85]
	v_pk_mul_f32 v[114:115], v[140:141], v[140:141]
	v_pk_add_f32 v[116:117], v[140:141], v[142:143]
	v_pk_mul_f32 v[110:111], v[132:133], v[132:133]
	v_pk_add_f32 v[112:113], v[132:133], v[134:135]
	v_pk_mul_f32 v[106:107], v[124:125], v[124:125]
	v_pk_add_f32 v[108:109], v[124:125], v[126:127]
	v_pk_fma_f32 v[118:119], v[84:85], v[84:85], v[118:119]
	v_pk_fma_f32 v[114:115], v[142:143], v[142:143], v[114:115]
	v_pk_fma_f32 v[110:111], v[134:135], v[134:135], v[110:111]
	v_pk_fma_f32 v[106:107], v[126:127], v[126:127], v[106:107]
	v_pk_fma_f32 v[118:119], v[86:87], v[86:87], v[118:119]
	v_pk_add_f32 v[120:121], v[120:121], v[86:87]
	v_pk_fma_f32 v[114:115], v[144:145], v[144:145], v[114:115]
	v_pk_add_f32 v[116:117], v[116:117], v[144:145]
	v_pk_fma_f32 v[110:111], v[136:137], v[136:137], v[110:111]
	v_pk_add_f32 v[112:113], v[112:113], v[136:137]
	v_pk_fma_f32 v[106:107], v[128:129], v[128:129], v[106:107]
	v_pk_add_f32 v[108:109], v[108:109], v[128:129]
	v_pk_fma_f32 v[118:119], v[88:89], v[88:89], v[118:119]
	v_pk_add_f32 v[120:121], v[120:121], v[88:89]
	v_pk_fma_f32 v[114:115], v[146:147], v[146:147], v[114:115]
	v_pk_add_f32 v[116:117], v[116:117], v[146:147]
	v_pk_fma_f32 v[110:111], v[138:139], v[138:139], v[110:111]
	v_pk_add_f32 v[112:113], v[112:113], v[138:139]
	v_pk_fma_f32 v[106:107], v[130:131], v[130:131], v[106:107]
	v_pk_add_f32 v[108:109], v[108:109], v[130:131]
	v_add_f32_e32 v118, v118, v119
	v_add_f32_e32 v114, v114, v115
	v_add_f32_e32 v110, v110, v111
	v_add_f32_e32 v106, v106, v107
	v_add_f32_e32 v119, v120, v121
	v_add_f32_e32 v115, v116, v117
	v_add_f32_e32 v111, v112, v113
	v_add_f32_e32 v107, v108, v109
	v_cndmask_b32_e64 v118, 0, v118, s[38:39]
	v_cndmask_b32_e64 v119, 0, v119, s[38:39]
	v_cndmask_b32_e64 v114, 0, v114, s[38:39]
	v_cndmask_b32_e64 v115, 0, v115, s[38:39]
	v_cndmask_b32_e64 v110, 0, v110, s[38:39]
	v_cndmask_b32_e64 v111, 0, v111, s[38:39]
	v_cndmask_b32_e64 v106, 0, v106, s[38:39]
	v_cndmask_b32_e64 v107, 0, v107, s[38:39]
	s_nop 1
	v_add_f32_dpp v118, v118, v118 quad_perm:[1,0,3,2] row_mask:0xf bank_mask:0xf
	v_add_f32_dpp v119, v119, v119 quad_perm:[1,0,3,2] row_mask:0xf bank_mask:0xf
	v_add_f32_dpp v114, v114, v114 quad_perm:[1,0,3,2] row_mask:0xf bank_mask:0xf
	v_add_f32_dpp v115, v115, v115 quad_perm:[1,0,3,2] row_mask:0xf bank_mask:0xf
	v_add_f32_dpp v110, v110, v110 quad_perm:[1,0,3,2] row_mask:0xf bank_mask:0xf
	v_add_f32_dpp v111, v111, v111 quad_perm:[1,0,3,2] row_mask:0xf bank_mask:0xf
	v_add_f32_dpp v106, v106, v106 quad_perm:[1,0,3,2] row_mask:0xf bank_mask:0xf
	v_add_f32_dpp v107, v107, v107 quad_perm:[1,0,3,2] row_mask:0xf bank_mask:0xf
	v_add_f32_dpp v118, v118, v118 quad_perm:[2,3,0,1] row_mask:0xf bank_mask:0xf
	v_add_f32_dpp v119, v119, v119 quad_perm:[2,3,0,1] row_mask:0xf bank_mask:0xf
	v_add_f32_dpp v114, v114, v114 quad_perm:[2,3,0,1] row_mask:0xf bank_mask:0xf
	v_add_f32_dpp v115, v115, v115 quad_perm:[2,3,0,1] row_mask:0xf bank_mask:0xf
	v_add_f32_dpp v110, v110, v110 quad_perm:[2,3,0,1] row_mask:0xf bank_mask:0xf
	v_add_f32_dpp v111, v111, v111 quad_perm:[2,3,0,1] row_mask:0xf bank_mask:0xf
	v_add_f32_dpp v106, v106, v106 quad_perm:[2,3,0,1] row_mask:0xf bank_mask:0xf
	v_add_f32_dpp v107, v107, v107 quad_perm:[2,3,0,1] row_mask:0xf bank_mask:0xf
	v_add_f32_dpp v118, v118, v118 row_half_mirror row_mask:0xf bank_mask:0xf
	v_add_f32_dpp v119, v119, v119 row_half_mirror row_mask:0xf bank_mask:0xf
	v_add_f32_dpp v114, v114, v114 row_half_mirror row_mask:0xf bank_mask:0xf
	v_add_f32_dpp v115, v115, v115 row_half_mirror row_mask:0xf bank_mask:0xf
	v_add_f32_dpp v110, v110, v110 row_half_mirror row_mask:0xf bank_mask:0xf
	v_add_f32_dpp v111, v111, v111 row_half_mirror row_mask:0xf bank_mask:0xf
	v_add_f32_dpp v106, v106, v106 row_half_mirror row_mask:0xf bank_mask:0xf
	v_add_f32_dpp v107, v107, v107 row_half_mirror row_mask:0xf bank_mask:0xf
	v_add_f32_dpp v118, v118, v118 row_mirror row_mask:0xf bank_mask:0xf
	v_add_f32_dpp v119, v119, v119 row_mirror row_mask:0xf bank_mask:0xf
	v_add_f32_dpp v114, v114, v114 row_mirror row_mask:0xf bank_mask:0xf
	v_add_f32_dpp v115, v115, v115 row_mirror row_mask:0xf bank_mask:0xf
	v_add_f32_dpp v110, v110, v110 row_mirror row_mask:0xf bank_mask:0xf
	v_add_f32_dpp v111, v111, v111 row_mirror row_mask:0xf bank_mask:0xf
	v_add_f32_dpp v106, v106, v106 row_mirror row_mask:0xf bank_mask:0xf
	v_add_f32_dpp v107, v107, v107 row_mirror row_mask:0xf bank_mask:0xf
	v_add_f32_dpp v118, v118, v118 row_bcast:15 row_mask:0xa bank_mask:0xf
	v_add_f32_dpp v119, v119, v119 row_bcast:15 row_mask:0xa bank_mask:0xf
	v_add_f32_dpp v114, v114, v114 row_bcast:15 row_mask:0xa bank_mask:0xf
	v_add_f32_dpp v115, v115, v115 row_bcast:15 row_mask:0xa bank_mask:0xf
	v_add_f32_dpp v110, v110, v110 row_bcast:15 row_mask:0xa bank_mask:0xf
	v_add_f32_dpp v111, v111, v111 row_bcast:15 row_mask:0xa bank_mask:0xf
	v_add_f32_dpp v106, v106, v106 row_bcast:15 row_mask:0xa bank_mask:0xf
	v_add_f32_dpp v107, v107, v107 row_bcast:15 row_mask:0xa bank_mask:0xf
	v_add_f32_dpp v118, v118, v118 row_bcast:31 row_mask:0xc bank_mask:0xf
	v_add_f32_dpp v119, v119, v119 row_bcast:31 row_mask:0xc bank_mask:0xf
	v_add_f32_dpp v114, v114, v114 row_bcast:31 row_mask:0xc bank_mask:0xf
	v_add_f32_dpp v115, v115, v115 row_bcast:31 row_mask:0xc bank_mask:0xf
	v_add_f32_dpp v110, v110, v110 row_bcast:31 row_mask:0xc bank_mask:0xf
	v_add_f32_dpp v111, v111, v111 row_bcast:31 row_mask:0xc bank_mask:0xf
	v_add_f32_dpp v106, v106, v106 row_bcast:31 row_mask:0xc bank_mask:0xf
	v_add_f32_dpp v107, v107, v107 row_bcast:31 row_mask:0xc bank_mask:0xf
	s_nop 0
	v_readlane_b32 s2, v118, 63
	v_readlane_b32 s3, v119, 63
	v_readlane_b32 s10, v114, 63
	v_readlane_b32 s11, v115, 63
	v_mov_b32_e32 v120, 0
	v_mov_b32_e32 v121, 0
	v_mov_b32_e32 v116, 0
	v_mov_b32_e32 v117, 0
	v_mov_b32_e32 v118, s2
	v_mov_b32_e32 v119, s3
	v_mov_b32_e32 v114, s10
	v_mov_b32_e32 v115, s11
	s_nop 0
	v_readlane_b32 s2, v110, 63
	v_readlane_b32 s3, v111, 63
	v_readlane_b32 s10, v106, 63
	v_readlane_b32 s11, v107, 63
	v_mov_b32_e32 v112, 0
	v_mov_b32_e32 v113, 0
	v_mov_b32_e32 v108, 0
	v_mov_b32_e32 v109, 0
	v_mov_b32_e32 v110, s2
	v_mov_b32_e32 v111, s3
	v_mov_b32_e32 v106, s10
	v_mov_b32_e32 v107, s11
	s_and_saveexec_b64 s[12:13], s[38:39]
	s_cbranch_execz .LBB0_842
	v_mov_b64_e32 v[90:91], v[194:195]
	v_mov_b64_e32 v[92:93], v[196:197]
	v_mov_b64_e32 v[98:99], v[198:199]
	v_mov_b64_e32 v[100:101], v[200:201]
	v_mov_b64_e32 v[94:95], v[202:203]
	v_mov_b64_e32 v[96:97], v[204:205]
	v_mov_b64_e32 v[102:103], v[206:207]
	v_mov_b64_e32 v[104:105], v[208:209]
	v_pk_add_f32 v[118:119], v[118:119], v[120:121]
	s_mov_b32 s2, 0x3b2aaaab
	v_pk_mul_f32 v[118:119], v[118:119], s[2:3] op_sel_hi:[1,0]
	v_and_b32_e32 v150, 0xffff0000, v81
	v_fma_f32 v118, -v119, v119, v118
	v_max_f32_e32 v118, 0, v118
	v_add_f32_e32 v118, 0x358637bd, v118
	v_cmp_gt_f32_e32 vcc, s33, v118
	v_mul_f32_e32 v120, 0x4b800000, v118
	v_cndmask_b32_e32 v118, v118, v120, vcc
	v_rsq_f32_e32 v118, v118
	s_nop 0
	v_mul_f32_e32 v120, 0x45800000, v118
	v_cndmask_b32_e32 v118, v118, v120, vcc
	v_mul_f32_e64 v248, -v119, v118
	v_fma_f32 v89, v89, v118, v248
	v_fma_f32 v88, v88, v118, v248
	v_fma_f32 v87, v87, v118, v248
	v_lshlrev_b32_e32 v81, 16, v81
	v_fma_f32 v86, v86, v118, v248
	v_fma_f32 v85, v85, v118, v248
	v_fma_f32 v84, v84, v118, v248
	v_fma_f32 v83, v83, v118, v248
	v_fma_f32 v82, v82, v118, v248
	s_mov_b32 s10, s66
	s_mov_b32 s11, s67
	v_fma_f32 v85, v85, v97, v93
	v_fma_f32 v89, v89, v105, v101
	v_mul_f32_e32 v120, 0xbfb8aa3b, v89
	v_exp_f32_e32 v120, v120
	v_fma_f32 v88, v88, v104, v100
	v_fma_f32 v87, v87, v103, v99
	v_fma_f32 v86, v86, v102, v98
	v_add_f32_e32 v120, 1.0, v120
	v_rcp_f32_e32 v120, v120
	v_fma_f32 v84, v84, v96, v92
	v_fma_f32 v83, v83, v95, v91
	v_fma_f32 v82, v82, v94, v90
	v_mul_f32_e32 v89, v89, v120
	v_mul_f32_e32 v120, 0xbfb8aa3b, v88
	v_exp_f32_e32 v120, v120
	v_mul_f32_e32 v89, v89, v150
	v_add_f32_e32 v120, 1.0, v120
	v_rcp_f32_e32 v120, v120
	s_nop 0
	v_mul_f32_e32 v88, v88, v120
	v_mul_f32_e32 v120, 0xbfb8aa3b, v87
	v_exp_f32_e32 v120, v120
	v_mul_f32_e32 v81, v88, v81
	v_and_b32_e32 v88, 0xffff0000, v80
	v_lshlrev_b32_e32 v80, 16, v80
	v_add_f32_e32 v120, 1.0, v120
	v_rcp_f32_e32 v120, v120
	s_nop 0
	v_mul_f32_e32 v87, v87, v120
	v_mul_f32_e32 v87, v87, v88
	v_mul_f32_e32 v88, 0xbfb8aa3b, v86
	v_exp_f32_e32 v88, v88
	s_nop 0
	v_add_f32_e32 v88, 1.0, v88
	v_rcp_f32_e32 v88, v88
	s_nop 0
	v_mul_f32_e32 v86, v86, v88
	v_mul_f32_e32 v88, 0xbfb8aa3b, v85
	v_exp_f32_e32 v88, v88
	v_mul_f32_e32 v80, v86, v80
	v_and_b32_e32 v86, 0xffff0000, v79
	v_lshlrev_b32_e32 v79, 16, v79
	v_add_f32_e32 v88, 1.0, v88
	v_rcp_f32_e32 v88, v88
	s_nop 0
	v_mul_f32_e32 v85, v85, v88
	v_mul_f32_e32 v85, v85, v86
	v_mul_f32_e32 v86, 0xbfb8aa3b, v84
	v_exp_f32_e32 v86, v86
	s_nop 0
	v_add_f32_e32 v86, 1.0, v86
	v_rcp_f32_e32 v86, v86
	s_nop 0
	v_mul_f32_e32 v84, v84, v86
	v_mul_f32_e32 v86, 0xbfb8aa3b, v83
	v_exp_f32_e32 v86, v86
	v_mul_f32_e32 v79, v84, v79
	v_and_b32_e32 v84, 0xffff0000, v78
	v_lshlrev_b32_e32 v78, 16, v78
	v_add_f32_e32 v86, 1.0, v86
	v_rcp_f32_e32 v86, v86
	s_nop 0
	v_mul_f32_e32 v83, v83, v86
	v_mul_f32_e32 v83, v83, v84
	v_mul_f32_e32 v84, 0xbfb8aa3b, v82
	v_exp_f32_e32 v84, v84
	s_nop 0
	v_add_f32_e32 v84, 1.0, v84
	v_rcp_f32_e32 v84, v84
	s_nop 0
	v_mul_f32_e32 v82, v82, v84
	v_mul_f32_e32 v78, v82, v78
	v_cvt_pk_bf16_f32 v78, v78, v83
	v_cvt_pk_bf16_f32 v79, v79, v85
	v_cvt_pk_bf16_f32 v80, v80, v87
	v_cvt_pk_bf16_f32 v81, v81, v89
	buffer_store_dwordx4 v[78:81], v148, s[8:11], 0 offen sc1
	s_waitcnt lgkmcnt(4)
	s_nop 0
	v_pk_add_f32 v[78:79], v[114:115], v[116:117]
	v_and_b32_e32 v80, 0xffff0000, v77
	v_pk_mul_f32 v[78:79], v[78:79], s[2:3] op_sel_hi:[1,0]
	v_lshlrev_b32_e32 v77, 16, v77
	v_fma_f32 v78, -v79, v79, v78
	v_max_f32_e32 v78, 0, v78
	v_add_f32_e32 v78, 0x358637bd, v78
	v_cmp_gt_f32_e32 vcc, s33, v78
	v_mul_f32_e32 v81, 0x4b800000, v78
	s_nop 0
	v_cndmask_b32_e32 v78, v78, v81, vcc
	v_rsq_f32_e32 v78, v78
	s_nop 0
	v_mul_f32_e32 v81, 0x45800000, v78
	v_cndmask_b32_e32 v78, v78, v81, vcc
	v_mul_f32_e64 v249, -v79, v78
	v_fma_f32 v81, v147, v78, v249
	v_fma_f32 v81, v81, v105, v101
	v_mul_f32_e32 v82, 0xbfb8aa3b, v81
	v_exp_f32_e32 v82, v82
	s_nop 0
	v_add_f32_e32 v82, 1.0, v82
	v_rcp_f32_e32 v82, v82
	s_nop 0
	v_mul_f32_e32 v81, v81, v82
	v_mul_f32_e32 v80, v81, v80
	v_fma_f32 v81, v146, v78, v249
	v_fma_f32 v81, v81, v104, v100
	v_mul_f32_e32 v82, 0xbfb8aa3b, v81
	v_exp_f32_e32 v82, v82
	s_nop 0
	v_add_f32_e32 v82, 1.0, v82
	v_rcp_f32_e32 v82, v82
	s_nop 0
	v_mul_f32_e32 v81, v81, v82
	v_fma_f32 v82, v145, v78, v249
	v_fma_f32 v82, v82, v103, v99
	v_mul_f32_e32 v83, 0xbfb8aa3b, v82
	v_exp_f32_e32 v83, v83
	v_mul_f32_e32 v77, v81, v77
	v_and_b32_e32 v81, 0xffff0000, v76
	v_lshlrev_b32_e32 v76, 16, v76
	v_add_f32_e32 v83, 1.0, v83
	v_rcp_f32_e32 v83, v83
	s_nop 0
	v_mul_f32_e32 v82, v82, v83
	v_mul_f32_e32 v81, v82, v81
	v_fma_f32 v82, v144, v78, v249
	v_fma_f32 v82, v82, v102, v98
	v_mul_f32_e32 v83, 0xbfb8aa3b, v82
	v_exp_f32_e32 v83, v83
	s_nop 0
	v_add_f32_e32 v83, 1.0, v83
	v_rcp_f32_e32 v83, v83
	s_nop 0
	v_mul_f32_e32 v82, v82, v83
	v_fma_f32 v83, v143, v78, v249
	v_fma_f32 v83, v83, v97, v93
	v_mul_f32_e32 v84, 0xbfb8aa3b, v83
	v_exp_f32_e32 v84, v84
	v_mul_f32_e32 v76, v82, v76
	v_and_b32_e32 v82, 0xffff0000, v75
	v_lshlrev_b32_e32 v75, 16, v75
	v_add_f32_e32 v84, 1.0, v84
	v_rcp_f32_e32 v84, v84
	s_nop 0
	v_mul_f32_e32 v83, v83, v84
	v_mul_f32_e32 v82, v83, v82
	v_fma_f32 v83, v142, v78, v249
	v_fma_f32 v83, v83, v96, v92
	v_mul_f32_e32 v84, 0xbfb8aa3b, v83
	v_exp_f32_e32 v84, v84
	s_nop 0
	v_add_f32_e32 v84, 1.0, v84
	v_rcp_f32_e32 v84, v84
	s_nop 0
	v_mul_f32_e32 v83, v83, v84
	v_fma_f32 v84, v141, v78, v249
	v_fma_f32 v78, v140, v78, v249
	v_fma_f32 v78, v78, v94, v90
	v_fma_f32 v84, v84, v95, v91
	v_mul_f32_e32 v79, 0xbfb8aa3b, v78
	v_mul_f32_e32 v85, 0xbfb8aa3b, v84
	v_exp_f32_e32 v79, v79
	v_exp_f32_e32 v85, v85
	v_mul_f32_e32 v75, v83, v75
	v_and_b32_e32 v83, 0xffff0000, v74
	v_add_f32_e32 v79, 1.0, v79
	v_add_f32_e32 v85, 1.0, v85
	v_rcp_f32_e32 v79, v79
	v_rcp_f32_e32 v85, v85
	v_lshlrev_b32_e32 v74, 16, v74
	v_mul_f32_e32 v78, v78, v79
	v_mul_f32_e32 v84, v84, v85
	v_mul_f32_e32 v74, v78, v74
	v_mul_f32_e32 v83, v84, v83
	v_cvt_pk_bf16_f32 v74, v74, v83
	v_cvt_pk_bf16_f32 v75, v75, v82
	v_cvt_pk_bf16_f32 v76, v76, v81
	v_cvt_pk_bf16_f32 v77, v77, v80
	buffer_store_dwordx4 v[74:77], v148, s[8:11], 0 offen offset:2048 sc1
	s_waitcnt lgkmcnt(2)
	s_nop 0
	v_pk_add_f32 v[74:75], v[110:111], v[112:113]
	v_and_b32_e32 v76, 0xffff0000, v73
	v_pk_mul_f32 v[74:75], v[74:75], s[2:3] op_sel_hi:[1,0]
	v_lshlrev_b32_e32 v73, 16, v73
	v_fma_f32 v74, -v75, v75, v74
	v_max_f32_e32 v74, 0, v74
	v_add_f32_e32 v74, 0x358637bd, v74
	v_cmp_gt_f32_e32 vcc, s33, v74
	v_mul_f32_e32 v77, 0x4b800000, v74
	s_nop 0
	v_cndmask_b32_e32 v74, v74, v77, vcc
	v_rsq_f32_e32 v74, v74
	s_nop 0
	v_mul_f32_e32 v77, 0x45800000, v74
	v_cndmask_b32_e32 v74, v74, v77, vcc
	v_mul_f32_e64 v250, -v75, v74
	v_fma_f32 v77, v139, v74, v250
	v_fma_f32 v77, v77, v105, v101
	v_mul_f32_e32 v78, 0xbfb8aa3b, v77
	v_exp_f32_e32 v78, v78
	s_nop 0
	v_add_f32_e32 v78, 1.0, v78
	v_rcp_f32_e32 v78, v78
	s_nop 0
	v_mul_f32_e32 v77, v77, v78
	v_mul_f32_e32 v76, v77, v76
	v_fma_f32 v77, v138, v74, v250
	v_fma_f32 v77, v77, v104, v100
	v_mul_f32_e32 v78, 0xbfb8aa3b, v77
	v_exp_f32_e32 v78, v78
	s_nop 0
	v_add_f32_e32 v78, 1.0, v78
	v_rcp_f32_e32 v78, v78
	s_nop 0
	v_mul_f32_e32 v77, v77, v78
	v_fma_f32 v78, v137, v74, v250
	v_fma_f32 v78, v78, v103, v99
	v_mul_f32_e32 v79, 0xbfb8aa3b, v78
	v_exp_f32_e32 v79, v79
	v_mul_f32_e32 v73, v77, v73
	v_and_b32_e32 v77, 0xffff0000, v72
	v_lshlrev_b32_e32 v72, 16, v72
	v_add_f32_e32 v79, 1.0, v79
	v_rcp_f32_e32 v79, v79
	s_nop 0
	v_mul_f32_e32 v78, v78, v79
	v_mul_f32_e32 v77, v78, v77
	v_fma_f32 v78, v136, v74, v250
	v_fma_f32 v78, v78, v102, v98
	v_mul_f32_e32 v79, 0xbfb8aa3b, v78
	v_exp_f32_e32 v79, v79
	s_nop 0
	v_add_f32_e32 v79, 1.0, v79
	v_rcp_f32_e32 v79, v79
	s_nop 0
	v_mul_f32_e32 v78, v78, v79
	v_fma_f32 v79, v135, v74, v250
	v_fma_f32 v79, v79, v97, v93
	v_mul_f32_e32 v80, 0xbfb8aa3b, v79
	v_exp_f32_e32 v80, v80
	v_mul_f32_e32 v72, v78, v72
	v_and_b32_e32 v78, 0xffff0000, v71
	v_lshlrev_b32_e32 v71, 16, v71
	v_add_f32_e32 v80, 1.0, v80
	v_rcp_f32_e32 v80, v80
	s_nop 0
	v_mul_f32_e32 v79, v79, v80
	v_mul_f32_e32 v78, v79, v78
	v_fma_f32 v79, v134, v74, v250
	v_fma_f32 v79, v79, v96, v92
	v_mul_f32_e32 v80, 0xbfb8aa3b, v79
	v_exp_f32_e32 v80, v80
	s_nop 0
	v_add_f32_e32 v80, 1.0, v80
	v_rcp_f32_e32 v80, v80
	s_nop 0
	v_mul_f32_e32 v79, v79, v80
	v_fma_f32 v80, v133, v74, v250
	v_fma_f32 v74, v132, v74, v250
	v_fma_f32 v74, v74, v94, v90
	v_fma_f32 v80, v80, v95, v91
	v_mul_f32_e32 v75, 0xbfb8aa3b, v74
	v_mul_f32_e32 v81, 0xbfb8aa3b, v80
	v_exp_f32_e32 v75, v75
	v_exp_f32_e32 v81, v81
	v_mul_f32_e32 v71, v79, v71
	v_and_b32_e32 v79, 0xffff0000, v70
	v_add_f32_e32 v75, 1.0, v75
	v_add_f32_e32 v81, 1.0, v81
	v_rcp_f32_e32 v75, v75
	v_rcp_f32_e32 v81, v81
	v_lshlrev_b32_e32 v70, 16, v70
	v_mul_f32_e32 v74, v74, v75
	v_mul_f32_e32 v80, v80, v81
	v_mul_f32_e32 v70, v74, v70
	v_mul_f32_e32 v79, v80, v79
	v_cvt_pk_bf16_f32 v70, v70, v79
	v_cvt_pk_bf16_f32 v71, v71, v78
	v_cvt_pk_bf16_f32 v72, v72, v77
	v_cvt_pk_bf16_f32 v73, v73, v76
	buffer_store_dwordx4 v[70:73], v123, s[8:11], 0 offen sc1
	s_waitcnt lgkmcnt(0)
	s_nop 0
	v_pk_add_f32 v[70:71], v[106:107], v[108:109]
	v_and_b32_e32 v72, 0xffff0000, v61
	v_pk_mul_f32 v[70:71], v[70:71], s[2:3] op_sel_hi:[1,0]
	v_lshlrev_b32_e32 v61, 16, v61
	v_fma_f32 v70, -v71, v71, v70
	v_max_f32_e32 v70, 0, v70
	v_add_f32_e32 v70, 0x358637bd, v70
	v_cmp_gt_f32_e32 vcc, s33, v70
	v_mul_f32_e32 v73, 0x4b800000, v70
	s_nop 0
	v_cndmask_b32_e32 v70, v70, v73, vcc
	v_rsq_f32_e32 v70, v70
	s_nop 0
	v_mul_f32_e32 v73, 0x45800000, v70
	v_cndmask_b32_e32 v70, v70, v73, vcc
	v_mul_f32_e64 v251, -v71, v70
	v_fma_f32 v73, v131, v70, v251
	v_fma_f32 v73, v73, v105, v101
	v_mul_f32_e32 v74, 0xbfb8aa3b, v73
	v_exp_f32_e32 v74, v74
	s_nop 0
	v_add_f32_e32 v74, 1.0, v74
	v_rcp_f32_e32 v74, v74
	s_nop 0
	v_mul_f32_e32 v73, v73, v74
	v_mul_f32_e32 v72, v73, v72
	v_fma_f32 v73, v130, v70, v251
	v_fma_f32 v73, v73, v104, v100
	v_mul_f32_e32 v74, 0xbfb8aa3b, v73
	v_exp_f32_e32 v74, v74
	s_nop 0
	v_add_f32_e32 v74, 1.0, v74
	v_rcp_f32_e32 v74, v74
	s_nop 0
	v_mul_f32_e32 v73, v73, v74
	v_fma_f32 v74, v129, v70, v251
	v_fma_f32 v74, v74, v103, v99
	v_mul_f32_e32 v75, 0xbfb8aa3b, v74
	v_exp_f32_e32 v75, v75
	v_mul_f32_e32 v61, v73, v61
	v_and_b32_e32 v73, 0xffff0000, v60
	v_lshlrev_b32_e32 v60, 16, v60
	v_add_f32_e32 v75, 1.0, v75
	v_rcp_f32_e32 v75, v75
	s_nop 0
	v_mul_f32_e32 v74, v74, v75
	v_mul_f32_e32 v73, v74, v73
	v_fma_f32 v74, v128, v70, v251
	v_fmac_f32_e32 v98, v74, v102
	v_fma_f32 v75, v127, v70, v251
	v_mul_f32_e32 v74, 0xbfb8aa3b, v98
	v_fma_f32 v75, v75, v97, v93
	v_exp_f32_e32 v74, v74
	v_mul_f32_e32 v76, 0xbfb8aa3b, v75
	v_exp_f32_e32 v76, v76
	v_add_f32_e32 v74, 1.0, v74
	v_rcp_f32_e32 v74, v74
	v_add_f32_e32 v76, 1.0, v76
	v_rcp_f32_e32 v76, v76
	v_mul_f32_e32 v74, v98, v74
	v_mul_f32_e32 v60, v74, v60
	v_and_b32_e32 v74, 0xffff0000, v59
	v_mul_f32_e32 v75, v75, v76
	v_mul_f32_e32 v74, v75, v74
	v_fma_f32 v75, v126, v70, v251
	v_fma_f32 v75, v75, v96, v92
	v_mul_f32_e32 v76, 0xbfb8aa3b, v75
	v_exp_f32_e32 v76, v76
	v_lshlrev_b32_e32 v59, 16, v59
	v_add_f32_e32 v76, 1.0, v76
	v_rcp_f32_e32 v76, v76
	s_nop 0
	v_mul_f32_e32 v75, v75, v76
	v_fma_f32 v76, v125, v70, v251
	v_fma_f32 v70, v124, v70, v251
	v_fmac_f32_e32 v90, v70, v94
	v_fma_f32 v76, v76, v95, v91
	v_mul_f32_e32 v70, 0xbfb8aa3b, v90
	v_mul_f32_e32 v77, 0xbfb8aa3b, v76
	v_exp_f32_e32 v70, v70
	v_exp_f32_e32 v77, v77
	v_mul_f32_e32 v59, v75, v59
	v_and_b32_e32 v75, 0xffff0000, v58
	v_add_f32_e32 v70, 1.0, v70
	v_add_f32_e32 v77, 1.0, v77
	v_rcp_f32_e32 v70, v70
	v_rcp_f32_e32 v77, v77
	v_lshlrev_b32_e32 v58, 16, v58
	v_mul_f32_e32 v70, v90, v70
	v_mul_f32_e32 v76, v76, v77
	v_mul_f32_e32 v58, v70, v58
	v_mul_f32_e32 v75, v76, v75
	v_cvt_pk_bf16_f32 v58, v58, v75
	v_cvt_pk_bf16_f32 v59, v59, v74
	v_cvt_pk_bf16_f32 v60, v60, v73
	v_cvt_pk_bf16_f32 v61, v61, v72
	buffer_store_dwordx4 v[58:61], v123, s[8:11], 0 offen offset:2048 sc1
